# P8 residual epilogue: four full vmcnt(0) store drains made counted (4/8/12/16 stores stay in flight; residual loads still waited)
# baseline (speedup 1.0000x reference)
; #define SCHED_BAR() __builtin_amdgcn_sched_barrier(0)
;     __device__ __forceinline__ void operator()(const Acc& acc, const Unit& u, int wr, int wc, int fr, int fq) const {
;     ...
;             for (int m = 0; m < 4; ++m) {
;                 const int row = u.pm * 256 + ai * 128 + wr * 64 + m * 16 + fr; const int rr = row < MREAL ? row : 0;
;                 const float* res = ((MODE == 0) ? xin_row(P, rr) : (const float*)x1_row(P, rr)) + colb;
; #pragma unroll
;                 for (int bj = 0; bj < 2; ++bj)
; #pragma unroll
;                     for (int n = 0; n < 2; ++n) R[m][bj][n] = *(const f32x4*)(res + bj * 32 + n * 4);
;             }
;             SCHED_BAR();
; #pragma unroll
;             for (int m = 0; m < 4; ++m) {
;                 const int row = u.pm * 256 + ai * 128 + wr * 64 + m * 16 + fr;
;                 const bool ok = row < MREAL; const int rr = ok ? row : 0;
;                 float* dst = ((MODE == 2) ? y_row(P, rr) : x1_row(P, rr)) + colb;
;                 float part = 0.f;
; #pragma unroll
;                 for (int bj = 0; bj < 2; ++bj) {
;                     const f32x4 o0 = R[m][bj][0] + acc[ai][bj][m][0] * sc, o1 = R[m][bj][1] + acc[ai][bj][m][1] * sc;
;                     if (ok) {
;                         *(f32x4*)(dst + bj * 32) = o0; *(f32x4*)(dst + bj * 32 + 4) = o1;
.LBB0_1835:
	v_readlane_b32 s8, v254, 1
	v_cndmask_b32_e64 v200, v229, 0, vcc
	v_readlane_b32 s14, v254, 7
	v_readlane_b32 s15, v254, 8
	s_waitcnt vmcnt(12)
	v_pk_fma_f32 v[74:75], v[74:75], 0.5, v[138:139] op_sel_hi:[1,0,1]
	v_pk_fma_f32 v[72:73], v[72:73], 0.5, v[136:137] op_sel_hi:[1,0,1]
	v_lshl_add_u64 v[80:81], s[14:15], 0, v[200:201]
	v_lshl_add_u64 v[80:81], v[80:81], 0, v[216:217]
	v_lshl_add_u64 v[80:81], v[212:213], 2, v[80:81]
	v_pk_fma_f32 v[66:67], v[66:67], 0.5, v[130:131] op_sel_hi:[1,0,1]
	v_pk_fma_f32 v[64:65], v[64:65], 0.5, v[128:129] op_sel_hi:[1,0,1]
	v_readlane_b32 s9, v254, 2
	v_readlane_b32 s10, v254, 3
	v_readlane_b32 s11, v254, 4
	v_readlane_b32 s12, v254, 5
	v_readlane_b32 s13, v254, 6
	v_pk_fma_f32 v[78:79], v[78:79], 0.5, v[142:143] op_sel_hi:[1,0,1]
	v_pk_fma_f32 v[76:77], v[76:77], 0.5, v[140:141] op_sel_hi:[1,0,1]
	global_store_dwordx4 v[80:81], v[72:75], off nt
	global_store_dwordx4 v[80:81], v[76:79], off offset:16 nt
	v_pk_fma_f32 v[70:71], v[70:71], 0.5, v[134:135] op_sel_hi:[1,0,1]
	v_pk_fma_f32 v[68:69], v[68:69], 0.5, v[132:133] op_sel_hi:[1,0,1]
	global_store_dwordx4 v[80:81], v[64:67], off offset:128 nt
	global_store_dwordx4 v[80:81], v[68:71], off offset:144 nt
.LBB0_1836:
	s_or_b64 exec, exec, s[6:7]
	v_add_u32_e32 v64, 0x80, v230
	v_cmp_gt_i32_e64 s[16:17], s46, v64
	v_readlane_b32 s52, v254, 1
	v_readlane_b32 s58, v254, 7
	v_cndmask_b32_e64 v64, 0, v64, s[16:17]
	v_readlane_b32 s59, v254, 8
	v_add_u32_e32 v66, 0xffff8000, v64
	v_ashrrev_i32_e32 v65, 31, v64
	v_cmp_gt_i32_e64 s[14:15], s39, v64
	s_mov_b64 s[6:7], s[58:59]
	v_mov_b32_e32 v68, s43
	v_cndmask_b32_e64 v65, 0, v65, s[14:15]
	v_cndmask_b32_e64 v64, v66, v64, s[14:15]
	v_mov_b32_e32 v69, s7
	v_mov_b32_e32 v70, s42
	v_mov_b32_e32 v71, s6
	v_cndmask_b32_e64 v67, v68, v69, s[14:15]
	v_cndmask_b32_e64 v66, v70, v71, s[14:15]
	s_waitcnt vmcnt(16)
	v_lshlrev_b64 v[134:135], 12, v[64:65]
	v_lshl_add_u64 v[64:65], v[66:67], 0, v[134:135]
	v_lshl_add_u64 v[64:65], v[64:65], 0, v[214:215]
	global_load_dwordx4 v[124:127], v[64:65], off offset:16 nt
	global_load_dwordx4 v[120:123], v[64:65], off nt
	global_load_dwordx4 v[116:119], v[64:65], off offset:144 nt
	global_load_dwordx4 v[112:115], v[64:65], off offset:128 nt
	v_add_u32_e32 v64, 0x90, v230
	v_cmp_gt_i32_e64 s[12:13], s46, v64
	v_readlane_b32 s53, v254, 2
	v_readlane_b32 s54, v254, 3
	v_cndmask_b32_e64 v64, 0, v64, s[12:13]
	v_add_u32_e32 v66, 0xffff8000, v64
	v_ashrrev_i32_e32 v65, 31, v64
	v_cmp_gt_i32_e64 s[10:11], s39, v64
	v_readlane_b32 s55, v254, 4
	v_readlane_b32 s56, v254, 5
	v_cndmask_b32_e64 v65, 0, v65, s[10:11]
	v_cndmask_b32_e64 v64, v66, v64, s[10:11]
	v_cndmask_b32_e64 v67, v68, v69, s[10:11]
	v_cndmask_b32_e64 v66, v70, v71, s[10:11]
	v_lshlrev_b64 v[132:133], 12, v[64:65]
	v_lshl_add_u64 v[64:65], v[66:67], 0, v[132:133]
	v_lshl_add_u64 v[64:65], v[64:65], 0, v[214:215]
	global_load_dwordx4 v[108:111], v[64:65], off offset:16 nt
	global_load_dwordx4 v[104:107], v[64:65], off nt
	global_load_dwordx4 v[100:103], v[64:65], off offset:144 nt
	global_load_dwordx4 v[96:99], v[64:65], off offset:128 nt
	v_add_u32_e32 v64, 0xa0, v230
	v_cmp_gt_i32_e64 s[8:9], s46, v64
	v_readlane_b32 s57, v254, 6
	s_nop 0
	v_cndmask_b32_e64 v64, 0, v64, s[8:9]
	v_add_u32_e32 v66, 0xffff8000, v64
	v_ashrrev_i32_e32 v65, 31, v64
	v_cmp_gt_i32_e64 s[6:7], s39, v64
	s_nop 1
	v_cndmask_b32_e64 v65, 0, v65, s[6:7]
	v_cndmask_b32_e64 v64, v66, v64, s[6:7]
	v_cndmask_b32_e64 v67, v68, v69, s[6:7]
	v_cndmask_b32_e64 v66, v70, v71, s[6:7]
	v_lshlrev_b64 v[130:131], 12, v[64:65]
	v_lshl_add_u64 v[64:65], v[66:67], 0, v[130:131]
	v_lshl_add_u64 v[64:65], v[64:65], 0, v[214:215]
	global_load_dwordx4 v[92:95], v[64:65], off offset:16 nt
	global_load_dwordx4 v[88:91], v[64:65], off nt
	global_load_dwordx4 v[84:87], v[64:65], off offset:144 nt
	global_load_dwordx4 v[80:83], v[64:65], off offset:128 nt
	v_add_u32_e32 v64, 0xb0, v230
	v_cmp_gt_i32_e64 s[2:3], s46, v64
	s_nop 1
	v_cndmask_b32_e64 v64, 0, v64, s[2:3]
	v_add_u32_e32 v66, 0xffff8000, v64
	v_ashrrev_i32_e32 v65, 31, v64
	v_cmp_gt_i32_e32 vcc, s39, v64
	s_nop 1
	v_cndmask_b32_e32 v65, 0, v65, vcc
	v_cndmask_b32_e32 v64, v66, v64, vcc
	v_cndmask_b32_e32 v67, v68, v69, vcc
	v_cndmask_b32_e32 v66, v70, v71, vcc
	v_lshlrev_b64 v[128:129], 12, v[64:65]
	v_lshl_add_u64 v[64:65], v[66:67], 0, v[128:129]
	v_lshl_add_u64 v[64:65], v[64:65], 0, v[214:215]
	global_load_dwordx4 v[76:79], v[64:65], off offset:16 nt
	global_load_dwordx4 v[72:75], v[64:65], off nt
	global_load_dwordx4 v[68:71], v[64:65], off offset:144 nt
	s_nop 0
	global_load_dwordx4 v[64:67], v[64:65], off offset:128 nt
	s_and_saveexec_b64 s[28:29], s[16:17]
	s_cbranch_execnz .LBB0_1844
	s_or_b64 exec, exec, s[28:29]
	s_and_saveexec_b64 s[14:15], s[12:13]
	s_cbranch_execnz .LBB0_1845

;     __device__ __forceinline__ void operator()(const Acc& acc, const Unit& u, int wr, int wc, int fr, int fq) const {
;     ...
;             for (int m = 0; m < 4; ++m) {
;                 const int row = u.pm * 256 + ai * 128 + wr * 64 + m * 16 + fr;
;                 const bool ok = row < MREAL; const int rr = ok ? row : 0;
;                 float* dst = ((MODE == 2) ? y_row(P, rr) : x1_row(P, rr)) + colb;
;                 float part = 0.f;
; #pragma unroll
;                 for (int bj = 0; bj < 2; ++bj) {
;                     const f32x4 o0 = R[m][bj][0] + acc[ai][bj][m][0] * sc, o1 = R[m][bj][1] + acc[ai][bj][m][1] * sc;
;                     if (ok) {
;                         *(f32x4*)(dst + bj * 32) = o0; *(f32x4*)(dst + bj * 32 + 4) = o1;
.LBB0_1842:
	v_readlane_b32 s52, v254, 1
	v_cndmask_b32_e64 v200, v229, 0, s[10:11]
	v_readlane_b32 s58, v254, 7
	v_readlane_b32 s59, v254, 8
	s_waitcnt vmcnt(4)
	v_pk_fma_f32 v[106:107], v[106:107], 0.5, v[170:171] op_sel_hi:[1,0,1]
	v_pk_fma_f32 v[104:105], v[104:105], 0.5, v[168:169] op_sel_hi:[1,0,1]
	v_lshl_add_u64 v[112:113], s[58:59], 0, v[200:201]
	v_lshl_add_u64 v[112:113], v[112:113], 0, v[220:221]
	v_lshl_add_u64 v[112:113], v[212:213], 2, v[112:113]
	v_pk_fma_f32 v[98:99], v[98:99], 0.5, v[162:163] op_sel_hi:[1,0,1]
	v_pk_fma_f32 v[96:97], v[96:97], 0.5, v[160:161] op_sel_hi:[1,0,1]
	v_readlane_b32 s53, v254, 2
	v_readlane_b32 s54, v254, 3
	v_readlane_b32 s55, v254, 4
	v_readlane_b32 s56, v254, 5
	v_readlane_b32 s57, v254, 6
	v_pk_fma_f32 v[110:111], v[110:111], 0.5, v[174:175] op_sel_hi:[1,0,1]
	v_pk_fma_f32 v[108:109], v[108:109], 0.5, v[172:173] op_sel_hi:[1,0,1]
	global_store_dwordx4 v[112:113], v[104:107], off nt
	global_store_dwordx4 v[112:113], v[108:111], off offset:16 nt
	v_pk_fma_f32 v[102:103], v[102:103], 0.5, v[166:167] op_sel_hi:[1,0,1]
	v_pk_fma_f32 v[100:101], v[100:101], 0.5, v[164:165] op_sel_hi:[1,0,1]
	global_store_dwordx4 v[112:113], v[96:99], off offset:128 nt
	global_store_dwordx4 v[112:113], v[100:103], off offset:144 nt
	s_or_b64 exec, exec, s[14:15]
	s_and_saveexec_b64 s[10:11], s[8:9]
	s_cbranch_execz .LBB0_1834
.LBB0_1843:
	v_readlane_b32 s52, v254, 1
	v_cndmask_b32_e64 v200, v229, 0, s[6:7]
	v_readlane_b32 s58, v254, 7
	v_readlane_b32 s59, v254, 8
	s_waitcnt vmcnt(8)
	v_pk_fma_f32 v[90:91], v[90:91], 0.5, v[154:155] op_sel_hi:[1,0,1]
	v_pk_fma_f32 v[88:89], v[88:89], 0.5, v[152:153] op_sel_hi:[1,0,1]
	v_lshl_add_u64 v[96:97], s[58:59], 0, v[200:201]
	v_lshl_add_u64 v[96:97], v[96:97], 0, v[218:219]
	v_lshl_add_u64 v[96:97], v[212:213], 2, v[96:97]
	v_pk_fma_f32 v[82:83], v[82:83], 0.5, v[146:147] op_sel_hi:[1,0,1]
	v_pk_fma_f32 v[80:81], v[80:81], 0.5, v[144:145] op_sel_hi:[1,0,1]
	v_readlane_b32 s53, v254, 2
	v_readlane_b32 s54, v254, 3
	v_readlane_b32 s55, v254, 4
	v_readlane_b32 s56, v254, 5
	v_readlane_b32 s57, v254, 6
	v_pk_fma_f32 v[94:95], v[94:95], 0.5, v[158:159] op_sel_hi:[1,0,1]
	v_pk_fma_f32 v[92:93], v[92:93], 0.5, v[156:157] op_sel_hi:[1,0,1]
	global_store_dwordx4 v[96:97], v[88:91], off nt
	global_store_dwordx4 v[96:97], v[92:95], off offset:16 nt
	v_pk_fma_f32 v[86:87], v[86:87], 0.5, v[150:151] op_sel_hi:[1,0,1]
	v_pk_fma_f32 v[84:85], v[84:85], 0.5, v[148:149] op_sel_hi:[1,0,1]
	global_store_dwordx4 v[96:97], v[80:83], off offset:128 nt
	global_store_dwordx4 v[96:97], v[84:87], off offset:144 nt
	s_or_b64 exec, exec, s[10:11]
	s_and_saveexec_b64 s[6:7], s[2:3]
	s_cbranch_execnz .LBB0_1835
	s_branch .LBB0_1836
